# v49 plus: attention softmax subtract as 16 packed v_pk_add_f32 (bit-identical)
# baseline (speedup 1.0000x reference)
; #define MFMA(a, b, c) __builtin_amdgcn_mfma_f32_32x32x16_bf16((a), (b), (c), 0, 0, 0)
; DI void attn_item(const Params& p, int seq, int hd, int qblk, char* smem, int tid_) {
;     ...
;     float ps = 0.f;
; #pragma unroll
;     for (int kb2 = 0; kb2 < 2; kb2++)
; #pragma unroll
;       for (int i = 0; i < 16; i++) {
;         float pv = __builtin_amdgcn_exp2f(st[kb2][i] - m);
;         st[kb2][i] = pv;
;         ps += pv;
;       }
;     lsum += ps;
;     __builtin_amdgcn_sched_barrier(0);
; #pragma unroll
;     for (int g = 0; g < 16; g++) {
;       const int kb2 = g >> 3, c = (g >> 2) & 1;
;       unsigned pk[4];
; #pragma unroll
;       for (int j = 0; j < 4; j++) pk[j] = pack2(st[kb2][8 * c + 2 * j], st[kb2][8 * c + 2 * j + 1]);
;       u32x4 pu = {pk[0], pk[1], pk[2], pk[3]};
;       bf16x8 pf = __builtin_bit_cast(bf16x8, pu);
;       o[g & 3] = MFMA(vfr[g & 3], pf, o[g & 3]);
;       if (g + 4 < 16) vfr[g & 3] = VFRAG(g + 4);
;       __builtin_amdgcn_sched_barrier(0);
;     }
;     ...
;     if (kt + 1 < 32) {
;       u16* sKn = (u16*)(smem + ((kt + 1) & 1) * 45056);
;       u16* sVn = sKn + 64 * 200;
; #pragma unroll
;       for (int i = 0; i < 3; i++) *(u32x4*)(sKn + kl + 64 * i) = rk[i];
; #pragma unroll
;       for (int i = 0; i < 2; i++) *(u32x4*)(sVn + vl + 64 * i * 72) = rv[i];
;     }
;     __syncthreads();
;     if (kt + 2 < 32) {
; #pragma unroll
;       for (int i = 0; i < 3; i++) rk[i] = *(const u32x4*)(kg + (size_t)(kt + 2) * 64 * 768 + 64 * i);
; #pragma unroll
;       for (int i = 0; i < 2; i++) rv[i] = *(const u32x4*)(vg + (size_t)(64 * i) * 2048 + (kt + 2) * 64);
;     }
.LBB0_627:
	v_pk_add_f32 v[64:65], v[64:65], v[198:199] op_sel_hi:[1,0] neg_lo:[0,1] neg_hi:[0,1]
	v_pk_add_f32 v[66:67], v[66:67], v[198:199] op_sel_hi:[1,0] neg_lo:[0,1] neg_hi:[0,1]
	v_pk_add_f32 v[68:69], v[68:69], v[198:199] op_sel_hi:[1,0] neg_lo:[0,1] neg_hi:[0,1]
	v_pk_add_f32 v[70:71], v[70:71], v[198:199] op_sel_hi:[1,0] neg_lo:[0,1] neg_hi:[0,1]
	v_pk_add_f32 v[72:73], v[72:73], v[198:199] op_sel_hi:[1,0] neg_lo:[0,1] neg_hi:[0,1]
	v_pk_add_f32 v[74:75], v[74:75], v[198:199] op_sel_hi:[1,0] neg_lo:[0,1] neg_hi:[0,1]
	v_pk_add_f32 v[76:77], v[76:77], v[198:199] op_sel_hi:[1,0] neg_lo:[0,1] neg_hi:[0,1]
	v_pk_add_f32 v[78:79], v[78:79], v[198:199] op_sel_hi:[1,0] neg_lo:[0,1] neg_hi:[0,1]
	v_pk_add_f32 v[80:81], v[80:81], v[198:199] op_sel_hi:[1,0] neg_lo:[0,1] neg_hi:[0,1]
	v_pk_add_f32 v[82:83], v[82:83], v[198:199] op_sel_hi:[1,0] neg_lo:[0,1] neg_hi:[0,1]
	v_pk_add_f32 v[84:85], v[84:85], v[198:199] op_sel_hi:[1,0] neg_lo:[0,1] neg_hi:[0,1]
	v_pk_add_f32 v[86:87], v[86:87], v[198:199] op_sel_hi:[1,0] neg_lo:[0,1] neg_hi:[0,1]
	v_pk_add_f32 v[88:89], v[88:89], v[198:199] op_sel_hi:[1,0] neg_lo:[0,1] neg_hi:[0,1]
	v_pk_add_f32 v[90:91], v[90:91], v[198:199] op_sel_hi:[1,0] neg_lo:[0,1] neg_hi:[0,1]
	v_pk_add_f32 v[92:93], v[92:93], v[198:199] op_sel_hi:[1,0] neg_lo:[0,1] neg_hi:[0,1]
	v_pk_add_f32 v[94:95], v[94:95], v[198:199] op_sel_hi:[1,0] neg_lo:[0,1] neg_hi:[0,1]
	v_exp_f32_e32 v64, v64
	v_exp_f32_e32 v65, v65
	v_exp_f32_e32 v66, v66
	v_exp_f32_e32 v67, v67
	v_exp_f32_e32 v68, v68
	v_exp_f32_e32 v69, v69
	v_exp_f32_e32 v70, v70
	v_exp_f32_e32 v71, v71
	v_exp_f32_e32 v72, v72
	v_exp_f32_e32 v73, v73
	v_exp_f32_e32 v74, v74
	v_exp_f32_e32 v75, v75
	v_exp_f32_e32 v76, v76
	v_exp_f32_e32 v77, v77
	v_exp_f32_e32 v78, v78
	v_exp_f32_e32 v79, v79
	v_exp_f32_e32 v80, v80
	v_exp_f32_e32 v81, v81
	v_exp_f32_e32 v82, v82
	v_exp_f32_e32 v83, v83
	v_exp_f32_e32 v84, v84
	v_exp_f32_e32 v85, v85
	v_exp_f32_e32 v86, v86
	v_exp_f32_e32 v87, v87
	v_exp_f32_e32 v88, v88
	v_exp_f32_e32 v89, v89
	v_exp_f32_e32 v90, v90
	v_exp_f32_e32 v91, v91
	v_exp_f32_e32 v92, v92
	v_exp_f32_e32 v93, v93
	v_exp_f32_e32 v94, v94
	v_exp_f32_e32 v95, v95
	v_cvt_pk_bf16_f32 v200, v64, v65
	v_cvt_pk_bf16_f32 v201, v66, v67
	v_cvt_pk_bf16_f32 v202, v68, v69
	v_cvt_pk_bf16_f32 v203, v70, v71
	v_add3_u32 v199, s5, v195, v188
	s_waitcnt lgkmcnt(3)
	v_mfma_f32_32x32x16_bf16 v[48:63], v[176:179], v[200:203], v[48:63]
	v_add_f32_e32 v64, 0, v64
	v_add_f32_e32 v64, v65, v64
	ds_read_b128 v[176:179], v199 offset:25632
	s_waitcnt lgkmcnt(3)
	v_mfma_f32_32x32x16_bf16 v[32:47], v[172:175], v[200:203], v[32:47]
	v_add_f32_e32 v64, v66, v64
	v_add_f32_e32 v64, v67, v64
	ds_read_b128 v[172:175], v199 offset:30240
	s_waitcnt lgkmcnt(3)
	v_mfma_f32_32x32x16_bf16 v[16:31], v[168:171], v[200:203], v[16:31]
	v_add_f32_e32 v64, v68, v64
	v_add_f32_e32 v64, v69, v64
	ds_read_b128 v[168:171], v199 offset:34848
	s_waitcnt lgkmcnt(3)
	v_mfma_f32_32x32x16_bf16 v[0:15], v[164:167], v[200:203], v[0:15]
	v_add_f32_e32 v64, v70, v64
	v_add_f32_e32 v64, v71, v64
	ds_read_b128 v[164:167], v199 offset:39456
	v_cvt_pk_bf16_f32 v200, v72, v73
	v_cvt_pk_bf16_f32 v201, v74, v75
	v_cvt_pk_bf16_f32 v202, v76, v77
	v_cvt_pk_bf16_f32 v203, v78, v79
	s_waitcnt lgkmcnt(3)
	s_nop 0
	v_mfma_f32_32x32x16_bf16 v[48:63], v[176:179], v[200:203], v[48:63]
	v_add_f32_e32 v64, v72, v64
	v_add_f32_e32 v64, v73, v64
	ds_read_b128 v[176:179], v199 offset:25664
	s_waitcnt lgkmcnt(3)
	v_mfma_f32_32x32x16_bf16 v[32:47], v[172:175], v[200:203], v[32:47]
	v_add_f32_e32 v64, v74, v64
	v_add_f32_e32 v64, v75, v64
	ds_read_b128 v[172:175], v199 offset:30272
	s_waitcnt lgkmcnt(3)
	v_mfma_f32_32x32x16_bf16 v[16:31], v[168:171], v[200:203], v[16:31]
	v_add_f32_e32 v64, v76, v64
	v_add_f32_e32 v64, v77, v64
	ds_read_b128 v[168:171], v199 offset:34880
	s_waitcnt lgkmcnt(3)
	v_mfma_f32_32x32x16_bf16 v[0:15], v[164:167], v[200:203], v[0:15]
	v_add_f32_e32 v64, v78, v64
	v_add_f32_e32 v64, v79, v64
	ds_read_b128 v[164:167], v199 offset:39488
	v_cvt_pk_bf16_f32 v200, v80, v81
	v_cvt_pk_bf16_f32 v201, v82, v83
	v_cvt_pk_bf16_f32 v202, v84, v85
	v_cvt_pk_bf16_f32 v203, v86, v87
	s_waitcnt lgkmcnt(3)
	s_nop 0
	v_mfma_f32_32x32x16_bf16 v[48:63], v[176:179], v[200:203], v[48:63]
	v_add_f32_e32 v64, v80, v64
	v_add_f32_e32 v64, v81, v64
	ds_read_b128 v[176:179], v199 offset:25696
	s_waitcnt lgkmcnt(3)
	v_mfma_f32_32x32x16_bf16 v[32:47], v[172:175], v[200:203], v[32:47]
	v_add_f32_e32 v64, v82, v64
	v_add_f32_e32 v64, v83, v64
	ds_read_b128 v[172:175], v199 offset:30304
	s_waitcnt lgkmcnt(3)
	v_mfma_f32_32x32x16_bf16 v[16:31], v[168:171], v[200:203], v[16:31]
	v_add_f32_e32 v64, v84, v64
	v_add_f32_e32 v64, v85, v64
	ds_read_b128 v[168:171], v199 offset:34912
	s_waitcnt lgkmcnt(3)
	v_mfma_f32_32x32x16_bf16 v[0:15], v[164:167], v[200:203], v[0:15]
	v_add_f32_e32 v64, v86, v64
	v_add_f32_e32 v64, v87, v64
	ds_read_b128 v[164:167], v199 offset:39520
	v_cvt_pk_bf16_f32 v200, v88, v89
	v_cvt_pk_bf16_f32 v201, v90, v91
	v_cvt_pk_bf16_f32 v202, v92, v93
	v_cvt_pk_bf16_f32 v203, v94, v95
	s_waitcnt lgkmcnt(3)
	s_nop 0
	v_mfma_f32_32x32x16_bf16 v[48:63], v[176:179], v[200:203], v[48:63]
	v_add_f32_e32 v64, v88, v64
	v_add_f32_e32 v64, v89, v64
	s_waitcnt lgkmcnt(2)
	v_mfma_f32_32x32x16_bf16 v[32:47], v[172:175], v[200:203], v[32:47]
	v_add_f32_e32 v64, v90, v64
	v_add_f32_e32 v64, v91, v64
	s_waitcnt lgkmcnt(1)
	v_mfma_f32_32x32x16_bf16 v[16:31], v[168:171], v[200:203], v[16:31]
	v_add_f32_e32 v64, v92, v64
	v_add_f32_e32 v64, v93, v64
	s_waitcnt lgkmcnt(0)
	v_mfma_f32_32x32x16_bf16 v[0:15], v[164:167], v[200:203], v[0:15]
	v_add_f32_e32 v64, v94, v64
	v_add_f32_e32 v64, v95, v64
	v_add_f32_e32 v194, v194, v64
	s_add_i32 s5, s3, 1
	s_bitcmp1_b32 s5, 0
	s_cselect_b32 s1, 0xb000, 0
	s_add_i32 s1, s1, 0
	v_lshl_add_u32 v164, v182, 1, s1
	s_waitcnt vmcnt(4)
	ds_write_b128 v164, v[144:147]
	s_waitcnt vmcnt(3)
	ds_write_b128 v164, v[148:151] offset:128
	s_waitcnt vmcnt(2)
	ds_write_b128 v164, v[152:155] offset:256
	v_lshl_add_u32 v164, v196, 1, s1
	s_cmp_gt_u32 s3, 29
	s_waitcnt vmcnt(1)
	ds_write_b128 v164, v[156:159] offset:25600
	s_waitcnt vmcnt(0)
	ds_write_b128 v164, v[160:163] offset:34816
	s_waitcnt lgkmcnt(0)
	s_barrier
	v_add3_u32 v200, s1, v188, v197
	ds_read_b128 v[64:67], v200
	ds_read_b128 v[80:83], v200 offset:32
	ds_read_b128 v[84:87], v200 offset:64
	ds_read_b128 v[88:91], v200 offset:96
	s_cbranch_scc1 .LBB0_629
	global_load_dwordx4 v[144:147], v[186:187], off offset:-128
	global_load_dwordx4 v[148:151], v[186:187], off
	global_load_dwordx4 v[152:155], v[186:187], off offset:128
	global_load_dwordx4 v[156:159], v[184:185], off
	v_add_co_u32_e32 v160, vcc, 0x40000, v184
	s_nop 1
	v_addc_co_u32_e32 v161, vcc, 0, v185, vcc
	global_load_dwordx4 v[160:163], v[160:161], off
